# v21 plus de-serialised residual-add epilogues in all three residual GEMM phases
# speedup vs baseline: 1.0039x; 1.0001x over previous
; __device__ __forceinline__ unsigned cvt_pk_bf16(float lo, float hi) { const f32x2 v = {lo, hi}; return __builtin_bit_cast(unsigned, __builtin_convertvector(v, bf16x2_t)); }
;     __device__ __forceinline__ void operator()(const f32x4 (&acc)[2][2][4][2], const Unit& u, int wr, int wc, int fr_, int fq_) const {
;     ...
;         const int row0 = u.pm * 256 + wr * 64 + fr, col0 = u.pn * 256 + wc * 32 + 8 * fq;
; #pragma unroll
;         for (int ai = 0; ai < 2; ++ai)
; #pragma unroll
;             for (int m = 0; m < 4; ++m) {
;                 const int row = row0 + ai * 128 + m * 16; float sq = 0.f;
; #pragma unroll
;                 for (int bj = 0; bj < 2; ++bj) {
;                     const size_t off = (size_t)row * DM + col0 + bj * 128;
;                     f32x4 r0, r1;
;                     if (R) { r0 = *(const f32x4*)(R + off); r1 = *(const f32x4*)(R + off + 4); }
;                     else { const u32x4 rb = *(const u32x4*)(Rb + off); r0 = (f32x4){bflo(rb.x), bfhi(rb.x), bflo(rb.y), bfhi(rb.y)}; r1 = (f32x4){bflo(rb.z), bfhi(rb.z), bflo(rb.w), bfhi(rb.w)}; }
;                     const f32x4 o0 = r0 + acc[ai][bj][m][0] * scale, o1 = r1 + acc[ai][bj][m][1] * scale;
;                     sq += o0[0] * o0[0] + o0[1] * o0[1] + o0[2] * o0[2] + o0[3] * o0[3] + o1[0] * o1[0] + o1[1] * o1[1] + o1[2] * o1[2] + o1[3] * o1[3];
;                     u32x4 w; w.x = cvt_pk_bf16(o0[0], o0[1]); w.y = cvt_pk_bf16(o0[2], o0[3]); w.z = cvt_pk_bf16(o1[0], o1[1]); w.w = cvt_pk_bf16(o1[2], o1[3]);
;                     *(u32x4*)(Xb + off) = w;
;                 }
;                 sq += __shfl_xor(sq, 16); sq += __shfl_xor(sq, 32); if (fq == 0) atomicAdd(ssq + row, sq);
;             }
.LBB0_568:
	s_lshl_b32 s8, s70, 8
	s_add_i32 s8, s8, s42
	v_add_u32_e32 v142, s8, v145
	s_lshl_b32 s8, s69, 8
	s_or_b32 s8, s8, s43
	v_lshl_add_u32 v140, v144, 3, s8
	v_ashrrev_i32_e32 v143, 31, v142
	v_ashrrev_i32_e32 v141, 31, v140
	v_lshlrev_b64 v[160:161], 11, v[142:143]
	v_lshl_add_u64 v[160:161], v[160:161], 0, v[140:141]
	v_lshl_add_u64 v[162:163], v[160:161], 2, s[76:77]
	v_lshl_add_u64 v[164:165], v[160:161], 1, s[54:55]
	v_lshl_add_u64 v[140:141], v[142:143], 2, s[6:7]
	s_mov_b32 s8, 0x10000
	s_mov_b32 s9, 0
	v_xor_b32_e32 v151, 16, v150
	v_xor_b32_e32 v160, 32, v150
	v_lshlrev_b32_e32 v151, 2, v151
	v_lshlrev_b32_e32 v160, 2, v160
	global_load_dwordx4 v[174:177], v[162:163], off
	global_load_dwordx4 v[178:181], v[162:163], off offset:16
	global_load_dwordx4 v[182:185], v[162:163], off offset:512
	global_load_dwordx4 v[186:189], v[162:163], off offset:528
	v_lshl_add_u64 v[162:163], v[162:163], 0, s[8:9]
	v_lshl_add_u64 v[162:163], v[162:163], 0, s[8:9]
	global_load_dwordx4 v[190:193], v[162:163], off
	global_load_dwordx4 v[194:197], v[162:163], off offset:16
	global_load_dwordx4 v[198:201], v[162:163], off offset:512
	global_load_dwordx4 v[202:205], v[162:163], off offset:528
	v_lshl_add_u64 v[162:163], v[162:163], 0, s[8:9]
	v_lshl_add_u64 v[162:163], v[162:163], 0, s[8:9]
	global_load_dwordx4 v[206:209], v[162:163], off
	global_load_dwordx4 v[210:213], v[162:163], off offset:16
	global_load_dwordx4 v[214:217], v[162:163], off offset:512
	global_load_dwordx4 v[218:221], v[162:163], off offset:528
	v_lshl_add_u64 v[162:163], v[162:163], 0, s[8:9]
	v_lshl_add_u64 v[162:163], v[162:163], 0, s[8:9]
	global_load_dwordx4 v[224:227], v[162:163], off
	global_load_dwordx4 v[228:231], v[162:163], off offset:16
	global_load_dwordx4 v[232:235], v[162:163], off offset:512
	global_load_dwordx4 v[236:239], v[162:163], off offset:528
	s_waitcnt vmcnt(12)
	v_fma_f32 v174, v124, 0.5, v174
	v_fma_f32 v175, v125, 0.5, v175
	v_fma_f32 v176, v126, 0.5, v176
	v_fma_f32 v177, v127, 0.5, v177
	v_fma_f32 v178, v120, 0.5, v178
	v_fma_f32 v179, v121, 0.5, v179
	v_fma_f32 v180, v122, 0.5, v180
	v_fma_f32 v181, v123, 0.5, v181
	v_mul_f32_e32 v152, v174, v174
	v_fmac_f32_e32 v152, v175, v175
	v_fmac_f32_e32 v152, v176, v176
	v_fmac_f32_e32 v152, v177, v177
	v_fmac_f32_e32 v152, v178, v178
	v_fmac_f32_e32 v152, v179, v179
	v_fmac_f32_e32 v152, v180, v180
	v_fmac_f32_e32 v152, v181, v181
	v_cvt_pk_bf16_f32 v240, v174, v175
	v_cvt_pk_bf16_f32 v241, v176, v177
	v_cvt_pk_bf16_f32 v242, v178, v179
	v_cvt_pk_bf16_f32 v243, v180, v181
	global_store_dwordx4 v[164:165], v[240:243], off
	v_fma_f32 v182, v116, 0.5, v182
	v_fma_f32 v183, v117, 0.5, v183
	v_fma_f32 v184, v118, 0.5, v184
	v_fma_f32 v185, v119, 0.5, v185
	v_fma_f32 v186, v112, 0.5, v186
	v_fma_f32 v187, v113, 0.5, v187
	v_fma_f32 v188, v114, 0.5, v188
	v_fma_f32 v189, v115, 0.5, v189
	v_fmac_f32_e32 v152, v182, v182
	v_fmac_f32_e32 v152, v183, v183
	v_fmac_f32_e32 v152, v184, v184
	v_fmac_f32_e32 v152, v185, v185
	v_fmac_f32_e32 v152, v186, v186
	v_fmac_f32_e32 v152, v187, v187
	v_fmac_f32_e32 v152, v188, v188
	v_fmac_f32_e32 v152, v189, v189
	v_cvt_pk_bf16_f32 v244, v182, v183
	v_cvt_pk_bf16_f32 v245, v184, v185
	v_cvt_pk_bf16_f32 v246, v186, v187
	v_cvt_pk_bf16_f32 v247, v188, v189
	global_store_dwordx4 v[164:165], v[244:247], off offset:256
	v_lshl_add_u64 v[162:163], v[162:163], 0, s[8:9]
	v_lshl_add_u64 v[162:163], v[162:163], 0, s[8:9]
	v_lshl_add_u64 v[162:163], v[162:163], 0, s[8:9]
	v_lshl_add_u64 v[162:163], v[162:163], 0, s[8:9]
	v_lshl_add_u64 v[162:163], v[162:163], 0, s[8:9]
	v_lshl_add_u64 v[162:163], v[162:163], 0, s[8:9]
	v_lshl_add_u64 v[162:163], v[162:163], 0, s[8:9]
	v_lshl_add_u64 v[162:163], v[162:163], 0, s[8:9]
	v_lshl_add_u64 v[162:163], v[162:163], 0, s[8:9]
	v_lshl_add_u64 v[162:163], v[162:163], 0, s[8:9]
	global_load_dwordx4 v[174:177], v[162:163], off
	global_load_dwordx4 v[178:181], v[162:163], off offset:16
	global_load_dwordx4 v[182:185], v[162:163], off offset:512
	global_load_dwordx4 v[186:189], v[162:163], off offset:528
	s_waitcnt vmcnt(14)
	v_lshl_add_u64 v[164:165], v[164:165], 0, s[8:9]
	v_fma_f32 v190, v108, 0.5, v190
	v_fma_f32 v191, v109, 0.5, v191
	v_fma_f32 v192, v110, 0.5, v192
	v_fma_f32 v193, v111, 0.5, v193
	v_fma_f32 v194, v104, 0.5, v194
	v_fma_f32 v195, v105, 0.5, v195
	v_fma_f32 v196, v106, 0.5, v196
	v_fma_f32 v197, v107, 0.5, v197
	v_mul_f32_e32 v153, v190, v190
	v_fmac_f32_e32 v153, v191, v191
	v_fmac_f32_e32 v153, v192, v192
	v_fmac_f32_e32 v153, v193, v193
	v_fmac_f32_e32 v153, v194, v194
	v_fmac_f32_e32 v153, v195, v195
	v_fmac_f32_e32 v153, v196, v196
	v_fmac_f32_e32 v153, v197, v197
	v_cvt_pk_bf16_f32 v240, v190, v191
	v_cvt_pk_bf16_f32 v241, v192, v193
	v_cvt_pk_bf16_f32 v242, v194, v195
	v_cvt_pk_bf16_f32 v243, v196, v197
	global_store_dwordx4 v[164:165], v[240:243], off
	v_fma_f32 v198, v100, 0.5, v198
	v_fma_f32 v199, v101, 0.5, v199
	v_fma_f32 v200, v102, 0.5, v200
	v_fma_f32 v201, v103, 0.5, v201
	v_fma_f32 v202, v96, 0.5, v202
	v_fma_f32 v203, v97, 0.5, v203
	v_fma_f32 v204, v98, 0.5, v204
	v_fma_f32 v205, v99, 0.5, v205
	v_fmac_f32_e32 v153, v198, v198
	v_fmac_f32_e32 v153, v199, v199
	v_fmac_f32_e32 v153, v200, v200
	v_fmac_f32_e32 v153, v201, v201
	v_fmac_f32_e32 v153, v202, v202
	v_fmac_f32_e32 v153, v203, v203
	v_fmac_f32_e32 v153, v204, v204
	v_fmac_f32_e32 v153, v205, v205
	v_cvt_pk_bf16_f32 v244, v198, v199
	v_cvt_pk_bf16_f32 v245, v200, v201
	v_cvt_pk_bf16_f32 v246, v202, v203
	v_cvt_pk_bf16_f32 v247, v204, v205
	global_store_dwordx4 v[164:165], v[244:247], off offset:256
	v_lshl_add_u64 v[162:163], v[162:163], 0, s[8:9]
	v_lshl_add_u64 v[162:163], v[162:163], 0, s[8:9]
	global_load_dwordx4 v[190:193], v[162:163], off
	global_load_dwordx4 v[194:197], v[162:163], off offset:16
	global_load_dwordx4 v[198:201], v[162:163], off offset:512
	global_load_dwordx4 v[202:205], v[162:163], off offset:528
	s_waitcnt vmcnt(16)
; __device__ __forceinline__ unsigned cvt_pk_bf16(float lo, float hi) { const f32x2 v = {lo, hi}; return __builtin_bit_cast(unsigned, __builtin_convertvector(v, bf16x2_t)); }
;     __device__ __forceinline__ void operator()(const f32x4 (&acc)[2][2][4][2], const Unit& u, int wr, int wc, int fr_, int fq_) const {
;     ...
;         const int row0 = u.pm * 256 + wr * 64 + fr, col0 = u.pn * 256 + wc * 32 + 8 * fq;
; #pragma unroll
;         for (int ai = 0; ai < 2; ++ai)
; #pragma unroll
;             for (int m = 0; m < 4; ++m) {
;                 const int row = row0 + ai * 128 + m * 16; float sq = 0.f;
; #pragma unroll
;                 for (int bj = 0; bj < 2; ++bj) {
;                     const size_t off = (size_t)row * DM + col0 + bj * 128;
;                     f32x4 r0, r1;
;                     if (R) { r0 = *(const f32x4*)(R + off); r1 = *(const f32x4*)(R + off + 4); }
;                     else { const u32x4 rb = *(const u32x4*)(Rb + off); r0 = (f32x4){bflo(rb.x), bfhi(rb.x), bflo(rb.y), bfhi(rb.y)}; r1 = (f32x4){bflo(rb.z), bfhi(rb.z), bflo(rb.w), bfhi(rb.w)}; }
;                     const f32x4 o0 = r0 + acc[ai][bj][m][0] * scale, o1 = r1 + acc[ai][bj][m][1] * scale;
;                     sq += o0[0] * o0[0] + o0[1] * o0[1] + o0[2] * o0[2] + o0[3] * o0[3] + o1[0] * o1[0] + o1[1] * o1[1] + o1[2] * o1[2] + o1[3] * o1[3];
;                     u32x4 w; w.x = cvt_pk_bf16(o0[0], o0[1]); w.y = cvt_pk_bf16(o0[2], o0[3]); w.z = cvt_pk_bf16(o1[0], o1[1]); w.w = cvt_pk_bf16(o1[2], o1[3]);
;                     *(u32x4*)(Xb + off) = w;
;                 }
;                 sq += __shfl_xor(sq, 16); sq += __shfl_xor(sq, 32); if (fq == 0) atomicAdd(ssq + row, sq);
;             }
	v_lshl_add_u64 v[164:165], v[164:165], 0, s[8:9]
	v_fma_f32 v206, v92, 0.5, v206
	v_fma_f32 v207, v93, 0.5, v207
	v_fma_f32 v208, v94, 0.5, v208
	v_fma_f32 v209, v95, 0.5, v209
	v_fma_f32 v210, v88, 0.5, v210
	v_fma_f32 v211, v89, 0.5, v211
	v_fma_f32 v212, v90, 0.5, v212
	v_fma_f32 v213, v91, 0.5, v213
	v_mul_f32_e32 v154, v206, v206
	v_fmac_f32_e32 v154, v207, v207
	v_fmac_f32_e32 v154, v208, v208
	v_fmac_f32_e32 v154, v209, v209
	v_fmac_f32_e32 v154, v210, v210
	v_fmac_f32_e32 v154, v211, v211
	v_fmac_f32_e32 v154, v212, v212
	v_fmac_f32_e32 v154, v213, v213
	v_cvt_pk_bf16_f32 v240, v206, v207
	v_cvt_pk_bf16_f32 v241, v208, v209
	v_cvt_pk_bf16_f32 v242, v210, v211
	v_cvt_pk_bf16_f32 v243, v212, v213
	global_store_dwordx4 v[164:165], v[240:243], off
	v_fma_f32 v214, v84, 0.5, v214
	v_fma_f32 v215, v85, 0.5, v215
	v_fma_f32 v216, v86, 0.5, v216
	v_fma_f32 v217, v87, 0.5, v217
	v_fma_f32 v218, v80, 0.5, v218
	v_fma_f32 v219, v81, 0.5, v219
	v_fma_f32 v220, v82, 0.5, v220
	v_fma_f32 v221, v83, 0.5, v221
	v_fmac_f32_e32 v154, v214, v214
	v_fmac_f32_e32 v154, v215, v215
	v_fmac_f32_e32 v154, v216, v216
	v_fmac_f32_e32 v154, v217, v217
	v_fmac_f32_e32 v154, v218, v218
	v_fmac_f32_e32 v154, v219, v219
	v_fmac_f32_e32 v154, v220, v220
	v_fmac_f32_e32 v154, v221, v221
	v_cvt_pk_bf16_f32 v244, v214, v215
	v_cvt_pk_bf16_f32 v245, v216, v217
	v_cvt_pk_bf16_f32 v246, v218, v219
	v_cvt_pk_bf16_f32 v247, v220, v221
	global_store_dwordx4 v[164:165], v[244:247], off offset:256
	v_lshl_add_u64 v[162:163], v[162:163], 0, s[8:9]
	v_lshl_add_u64 v[162:163], v[162:163], 0, s[8:9]
	global_load_dwordx4 v[206:209], v[162:163], off
	global_load_dwordx4 v[210:213], v[162:163], off offset:16
	global_load_dwordx4 v[214:217], v[162:163], off offset:512
	global_load_dwordx4 v[218:221], v[162:163], off offset:528
	s_waitcnt vmcnt(18)
	v_lshl_add_u64 v[164:165], v[164:165], 0, s[8:9]
	v_fma_f32 v224, v76, 0.5, v224
	v_fma_f32 v225, v77, 0.5, v225
	v_fma_f32 v226, v78, 0.5, v226
	v_fma_f32 v227, v79, 0.5, v227
	v_fma_f32 v228, v72, 0.5, v228
	v_fma_f32 v229, v73, 0.5, v229
	v_fma_f32 v230, v74, 0.5, v230
	v_fma_f32 v231, v75, 0.5, v231
	v_mul_f32_e32 v155, v224, v224
	v_fmac_f32_e32 v155, v225, v225
	v_fmac_f32_e32 v155, v226, v226
	v_fmac_f32_e32 v155, v227, v227
	v_fmac_f32_e32 v155, v228, v228
	v_fmac_f32_e32 v155, v229, v229
	v_fmac_f32_e32 v155, v230, v230
	v_fmac_f32_e32 v155, v231, v231
	v_cvt_pk_bf16_f32 v240, v224, v225
	v_cvt_pk_bf16_f32 v241, v226, v227
	v_cvt_pk_bf16_f32 v242, v228, v229
	v_cvt_pk_bf16_f32 v243, v230, v231
	global_store_dwordx4 v[164:165], v[240:243], off
	v_fma_f32 v232, v68, 0.5, v232
	v_fma_f32 v233, v69, 0.5, v233
	v_fma_f32 v234, v70, 0.5, v234
	v_fma_f32 v235, v71, 0.5, v235
	v_fma_f32 v236, v64, 0.5, v236
	v_fma_f32 v237, v65, 0.5, v237
	v_fma_f32 v238, v66, 0.5, v238
	v_fma_f32 v239, v67, 0.5, v239
	v_fmac_f32_e32 v155, v232, v232
	v_fmac_f32_e32 v155, v233, v233
	v_fmac_f32_e32 v155, v234, v234
	v_fmac_f32_e32 v155, v235, v235
	v_fmac_f32_e32 v155, v236, v236
	v_fmac_f32_e32 v155, v237, v237
	v_fmac_f32_e32 v155, v238, v238
	v_fmac_f32_e32 v155, v239, v239
	v_cvt_pk_bf16_f32 v244, v232, v233
	v_cvt_pk_bf16_f32 v245, v234, v235
	v_cvt_pk_bf16_f32 v246, v236, v237
	v_cvt_pk_bf16_f32 v247, v238, v239
	global_store_dwordx4 v[164:165], v[244:247], off offset:256
	v_lshl_add_u64 v[162:163], v[162:163], 0, s[8:9]
	v_lshl_add_u64 v[162:163], v[162:163], 0, s[8:9]
	global_load_dwordx4 v[224:227], v[162:163], off
	global_load_dwordx4 v[228:231], v[162:163], off offset:16
	global_load_dwordx4 v[232:235], v[162:163], off offset:512
	global_load_dwordx4 v[236:239], v[162:163], off offset:528
	s_waitcnt vmcnt(18)
	v_lshl_add_u64 v[164:165], v[164:165], 0, s[8:9]
	v_lshl_add_u64 v[164:165], v[164:165], 0, s[8:9]
	v_lshl_add_u64 v[164:165], v[164:165], 0, s[8:9]
	v_lshl_add_u64 v[164:165], v[164:165], 0, s[8:9]
	v_lshl_add_u64 v[164:165], v[164:165], 0, s[8:9]
	v_fma_f32 v174, v60, 0.5, v174
	v_fma_f32 v175, v61, 0.5, v175
	v_fma_f32 v176, v62, 0.5, v176
	v_fma_f32 v177, v63, 0.5, v177
	v_fma_f32 v178, v56, 0.5, v178
	v_fma_f32 v179, v57, 0.5, v179
	v_fma_f32 v180, v58, 0.5, v180
	v_fma_f32 v181, v59, 0.5, v181
	v_mul_f32_e32 v156, v174, v174
	v_fmac_f32_e32 v156, v175, v175
	v_fmac_f32_e32 v156, v176, v176
	v_fmac_f32_e32 v156, v177, v177
	v_fmac_f32_e32 v156, v178, v178
	v_fmac_f32_e32 v156, v179, v179
	v_fmac_f32_e32 v156, v180, v180
	v_fmac_f32_e32 v156, v181, v181
	v_cvt_pk_bf16_f32 v240, v174, v175
	v_cvt_pk_bf16_f32 v241, v176, v177
	v_cvt_pk_bf16_f32 v242, v178, v179
	v_cvt_pk_bf16_f32 v243, v180, v181
	global_store_dwordx4 v[164:165], v[240:243], off
	v_fma_f32 v182, v52, 0.5, v182
	v_fma_f32 v183, v53, 0.5, v183
	v_fma_f32 v184, v54, 0.5, v184
	v_fma_f32 v185, v55, 0.5, v185
	v_fma_f32 v186, v48, 0.5, v186
	v_fma_f32 v187, v49, 0.5, v187
	v_fma_f32 v188, v50, 0.5, v188
	v_fma_f32 v189, v51, 0.5, v189
	v_fmac_f32_e32 v156, v182, v182
	v_fmac_f32_e32 v156, v183, v183
	v_fmac_f32_e32 v156, v184, v184
	v_fmac_f32_e32 v156, v185, v185
	v_fmac_f32_e32 v156, v186, v186
	v_fmac_f32_e32 v156, v187, v187
	v_fmac_f32_e32 v156, v188, v188
	v_fmac_f32_e32 v156, v189, v189
	v_cvt_pk_bf16_f32 v244, v182, v183
	v_cvt_pk_bf16_f32 v245, v184, v185
	v_cvt_pk_bf16_f32 v246, v186, v187
	v_cvt_pk_bf16_f32 v247, v188, v189
	global_store_dwordx4 v[164:165], v[244:247], off offset:256
	s_waitcnt vmcnt(14)
; __device__ __forceinline__ unsigned cvt_pk_bf16(float lo, float hi) { const f32x2 v = {lo, hi}; return __builtin_bit_cast(unsigned, __builtin_convertvector(v, bf16x2_t)); }
;     __device__ __forceinline__ void operator()(const f32x4 (&acc)[2][2][4][2], const Unit& u, int wr, int wc, int fr_, int fq_) const {
;     ...
;                 const int row = row0 + ai * 128 + m * 16; float sq = 0.f;
; #pragma unroll
;                 for (int bj = 0; bj < 2; ++bj) {
;                     const size_t off = (size_t)row * DM + col0 + bj * 128;
;                     f32x4 r0, r1;
;                     if (R) { r0 = *(const f32x4*)(R + off); r1 = *(const f32x4*)(R + off + 4); }
;                     else { const u32x4 rb = *(const u32x4*)(Rb + off); r0 = (f32x4){bflo(rb.x), bfhi(rb.x), bflo(rb.y), bfhi(rb.y)}; r1 = (f32x4){bflo(rb.z), bfhi(rb.z), bflo(rb.w), bfhi(rb.w)}; }
;                     const f32x4 o0 = r0 + acc[ai][bj][m][0] * scale, o1 = r1 + acc[ai][bj][m][1] * scale;
;                     sq += o0[0] * o0[0] + o0[1] * o0[1] + o0[2] * o0[2] + o0[3] * o0[3] + o1[0] * o1[0] + o1[1] * o1[1] + o1[2] * o1[2] + o1[3] * o1[3];
;                     u32x4 w; w.x = cvt_pk_bf16(o0[0], o0[1]); w.y = cvt_pk_bf16(o0[2], o0[3]); w.z = cvt_pk_bf16(o1[0], o1[1]); w.w = cvt_pk_bf16(o1[2], o1[3]);
;                     *(u32x4*)(Xb + off) = w;
;                 }
;                 sq += __shfl_xor(sq, 16); sq += __shfl_xor(sq, 32); if (fq == 0) atomicAdd(ssq + row, sq);
	v_lshl_add_u64 v[164:165], v[164:165], 0, s[8:9]
	v_fma_f32 v190, v44, 0.5, v190
	v_fma_f32 v191, v45, 0.5, v191
	v_fma_f32 v192, v46, 0.5, v192
	v_fma_f32 v193, v47, 0.5, v193
	v_fma_f32 v194, v40, 0.5, v194
	v_fma_f32 v195, v41, 0.5, v195
	v_fma_f32 v196, v42, 0.5, v196
	v_fma_f32 v197, v43, 0.5, v197
	v_mul_f32_e32 v157, v190, v190
	v_fmac_f32_e32 v157, v191, v191
	v_fmac_f32_e32 v157, v192, v192
	v_fmac_f32_e32 v157, v193, v193
	v_fmac_f32_e32 v157, v194, v194
	v_fmac_f32_e32 v157, v195, v195
	v_fmac_f32_e32 v157, v196, v196
	v_fmac_f32_e32 v157, v197, v197
	v_cvt_pk_bf16_f32 v240, v190, v191
	v_cvt_pk_bf16_f32 v241, v192, v193
	v_cvt_pk_bf16_f32 v242, v194, v195
	v_cvt_pk_bf16_f32 v243, v196, v197
	global_store_dwordx4 v[164:165], v[240:243], off
	v_fma_f32 v198, v36, 0.5, v198
	v_fma_f32 v199, v37, 0.5, v199
	v_fma_f32 v200, v38, 0.5, v200
	v_fma_f32 v201, v39, 0.5, v201
	v_fma_f32 v202, v32, 0.5, v202
	v_fma_f32 v203, v33, 0.5, v203
	v_fma_f32 v204, v34, 0.5, v204
	v_fma_f32 v205, v35, 0.5, v205
	v_fmac_f32_e32 v157, v198, v198
	v_fmac_f32_e32 v157, v199, v199
	v_fmac_f32_e32 v157, v200, v200
	v_fmac_f32_e32 v157, v201, v201
	v_fmac_f32_e32 v157, v202, v202
	v_fmac_f32_e32 v157, v203, v203
	v_fmac_f32_e32 v157, v204, v204
	v_fmac_f32_e32 v157, v205, v205
	v_cvt_pk_bf16_f32 v244, v198, v199
	v_cvt_pk_bf16_f32 v245, v200, v201
	v_cvt_pk_bf16_f32 v246, v202, v203
	v_cvt_pk_bf16_f32 v247, v204, v205
	global_store_dwordx4 v[164:165], v[244:247], off offset:256
	s_waitcnt vmcnt(10)
	v_lshl_add_u64 v[164:165], v[164:165], 0, s[8:9]
	v_fma_f32 v206, v28, 0.5, v206
	v_fma_f32 v207, v29, 0.5, v207
	v_fma_f32 v208, v30, 0.5, v208
	v_fma_f32 v209, v31, 0.5, v209
	v_fma_f32 v210, v24, 0.5, v210
	v_fma_f32 v211, v25, 0.5, v211
	v_fma_f32 v212, v26, 0.5, v212
	v_fma_f32 v213, v27, 0.5, v213
	v_mul_f32_e32 v158, v206, v206
	v_fmac_f32_e32 v158, v207, v207
	v_fmac_f32_e32 v158, v208, v208
	v_fmac_f32_e32 v158, v209, v209
	v_fmac_f32_e32 v158, v210, v210
	v_fmac_f32_e32 v158, v211, v211
	v_fmac_f32_e32 v158, v212, v212
	v_fmac_f32_e32 v158, v213, v213
	v_cvt_pk_bf16_f32 v240, v206, v207
	v_cvt_pk_bf16_f32 v241, v208, v209
	v_cvt_pk_bf16_f32 v242, v210, v211
	v_cvt_pk_bf16_f32 v243, v212, v213
	global_store_dwordx4 v[164:165], v[240:243], off
	v_fma_f32 v214, v20, 0.5, v214
	v_fma_f32 v215, v21, 0.5, v215
	v_fma_f32 v216, v22, 0.5, v216
	v_fma_f32 v217, v23, 0.5, v217
	v_fma_f32 v218, v16, 0.5, v218
	v_fma_f32 v219, v17, 0.5, v219
	v_fma_f32 v220, v18, 0.5, v220
	v_fma_f32 v221, v19, 0.5, v221
	v_fmac_f32_e32 v158, v214, v214
	v_fmac_f32_e32 v158, v215, v215
	v_fmac_f32_e32 v158, v216, v216
	v_fmac_f32_e32 v158, v217, v217
	v_fmac_f32_e32 v158, v218, v218
	v_fmac_f32_e32 v158, v219, v219
	v_fmac_f32_e32 v158, v220, v220
	v_fmac_f32_e32 v158, v221, v221
	v_cvt_pk_bf16_f32 v244, v214, v215
	v_cvt_pk_bf16_f32 v245, v216, v217
	v_cvt_pk_bf16_f32 v246, v218, v219
	v_cvt_pk_bf16_f32 v247, v220, v221
	global_store_dwordx4 v[164:165], v[244:247], off offset:256
	s_waitcnt vmcnt(6)
	v_lshl_add_u64 v[164:165], v[164:165], 0, s[8:9]
	v_fma_f32 v224, v12, 0.5, v224
	v_fma_f32 v225, v13, 0.5, v225
	v_fma_f32 v226, v14, 0.5, v226
	v_fma_f32 v227, v15, 0.5, v227
	v_fma_f32 v228, v8, 0.5, v228
	v_fma_f32 v229, v9, 0.5, v229
	v_fma_f32 v230, v10, 0.5, v230
	v_fma_f32 v231, v11, 0.5, v231
	v_mul_f32_e32 v159, v224, v224
	v_fmac_f32_e32 v159, v225, v225
	v_fmac_f32_e32 v159, v226, v226
	v_fmac_f32_e32 v159, v227, v227
	v_fmac_f32_e32 v159, v228, v228
	v_fmac_f32_e32 v159, v229, v229
	v_fmac_f32_e32 v159, v230, v230
	v_fmac_f32_e32 v159, v231, v231
	v_cvt_pk_bf16_f32 v240, v224, v225
	v_cvt_pk_bf16_f32 v241, v226, v227
	v_cvt_pk_bf16_f32 v242, v228, v229
	v_cvt_pk_bf16_f32 v243, v230, v231
	global_store_dwordx4 v[164:165], v[240:243], off
	v_fma_f32 v232, v4, 0.5, v232
	v_fma_f32 v233, v5, 0.5, v233
	v_fma_f32 v234, v6, 0.5, v234
	v_fma_f32 v235, v7, 0.5, v235
	v_fma_f32 v236, v0, 0.5, v236
	v_fma_f32 v237, v1, 0.5, v237
	v_fma_f32 v238, v2, 0.5, v238
	v_fma_f32 v239, v3, 0.5, v239
	v_fmac_f32_e32 v159, v232, v232
	v_fmac_f32_e32 v159, v233, v233
	v_fmac_f32_e32 v159, v234, v234
	v_fmac_f32_e32 v159, v235, v235
	v_fmac_f32_e32 v159, v236, v236
	v_fmac_f32_e32 v159, v237, v237
	v_fmac_f32_e32 v159, v238, v238
	v_fmac_f32_e32 v159, v239, v239
	v_cvt_pk_bf16_f32 v244, v232, v233
	v_cvt_pk_bf16_f32 v245, v234, v235
	v_cvt_pk_bf16_f32 v246, v236, v237
	v_cvt_pk_bf16_f32 v247, v238, v239
	global_store_dwordx4 v[164:165], v[244:247], off offset:256
	ds_bpermute_b32 v174, v151, v152
	ds_bpermute_b32 v175, v151, v153
	ds_bpermute_b32 v176, v151, v154
	ds_bpermute_b32 v177, v151, v155
	ds_bpermute_b32 v178, v151, v156
	ds_bpermute_b32 v179, v151, v157
	ds_bpermute_b32 v180, v151, v158
	ds_bpermute_b32 v181, v151, v159
	s_waitcnt lgkmcnt(0)
	v_add_f32_e32 v152, v152, v174
	v_add_f32_e32 v153, v153, v175
	v_add_f32_e32 v154, v154, v176
	v_add_f32_e32 v155, v155, v177
	v_add_f32_e32 v156, v156, v178
	v_add_f32_e32 v157, v157, v179
	v_add_f32_e32 v158, v158, v180
	v_add_f32_e32 v159, v159, v181
	ds_bpermute_b32 v174, v160, v152
	ds_bpermute_b32 v175, v160, v153
	ds_bpermute_b32 v176, v160, v154
	ds_bpermute_b32 v177, v160, v155
	ds_bpermute_b32 v178, v160, v156
	ds_bpermute_b32 v179, v160, v157
	ds_bpermute_b32 v180, v160, v158
	ds_bpermute_b32 v181, v160, v159
	s_waitcnt lgkmcnt(0)
	v_add_f32_e32 v152, v152, v174
	v_add_f32_e32 v153, v153, v175
	v_add_f32_e32 v154, v154, v176
	v_add_f32_e32 v155, v155, v177
	v_add_f32_e32 v156, v156, v178
	v_add_f32_e32 v157, v157, v179
	v_add_f32_e32 v158, v158, v180
	v_add_f32_e32 v159, v159, v181
	v_cmp_eq_u32_e32 vcc, 0, v144
	s_and_saveexec_b64 s[8:9], vcc
	s_cbranch_execz .LBB0_584
	global_atomic_add_f32 v[140:141], v152, off
	global_atomic_add_f32 v[140:141], v153, off offset:64
	global_atomic_add_f32 v[140:141], v154, off offset:128
	global_atomic_add_f32 v[140:141], v155, off offset:192
	global_atomic_add_f32 v[140:141], v156, off offset:512
	global_atomic_add_f32 v[140:141], v157, off offset:576
	global_atomic_add_f32 v[140:141], v158, off offset:640
	global_atomic_add_f32 v[140:141], v159, off offset:704
